# P6' panel rendezvous: one polling wave per workgroup (workgroup barriers around it) instead of 8; rest as best
# speedup vs baseline: 1.0021x; 1.0021x over previous
.LBB0_677:
	s_lshl_b32 s3, s2, 8
	s_add_i32 s3, s3, s77
	v_add_u32_e32 v181, s3, v172
	v_lshl_add_u32 v185, v173, 3, s44
	v_lshlrev_b32_e32 v253, 2, v181
	v_lshlrev_b32_e32 v252, 2, v185
	v_lshlrev_b32_e32 v187, 12, v181
	v_lshl_add_u32 v187, v185, 1, v187
	v_lshlrev_b32_e32 v181, 13, v181
	s_lshl_b32 s3, s44, 2
	v_lshl_add_u32 v185, v173, 4, s3
	v_add_u32_e32 v185, v185, v181
	global_load_dword v164, v253, s[12:13]
	global_load_dword v165, v253, s[12:13] offset:64
	global_load_dword v166, v253, s[12:13] offset:128
	global_load_dword v167, v253, s[12:13] offset:192
	global_load_dword v168, v253, s[12:13] offset:512
	global_load_dword v169, v253, s[12:13] offset:576
	global_load_dword v170, v253, s[12:13] offset:640
	global_load_dword v171, v253, s[12:13] offset:704
	global_load_dwordx4 v[148:151], v252, s[14:15] offset:0
	global_load_dwordx4 v[152:155], v252, s[14:15] offset:16
	global_load_dwordx4 v[156:159], v252, s[14:15] offset:512
	global_load_dwordx4 v[160:163], v252, s[14:15] offset:528
	s_mov_b32 s98, s18
	s_mov_b32 s99, s19
	s_nop 0
	global_load_dwordx4 v[188:191], v187, s[98:99]
	global_load_dwordx4 v[192:195], v187, s[98:99] offset:256
	s_add_u32 s98, s18, 0x10000
	s_addc_u32 s99, s19, 0
	s_nop 0
	global_load_dwordx4 v[196:199], v187, s[98:99]
	global_load_dwordx4 v[200:203], v187, s[98:99] offset:256
	s_add_u32 s98, s18, 0x20000
	s_addc_u32 s99, s19, 0
	s_nop 0
	global_load_dwordx4 v[204:207], v187, s[98:99]
	global_load_dwordx4 v[208:211], v187, s[98:99] offset:256
	s_add_u32 s98, s18, 0x30000
	s_addc_u32 s99, s19, 0
	s_nop 0
	global_load_dwordx4 v[212:215], v187, s[98:99]
	global_load_dwordx4 v[216:219], v187, s[98:99] offset:256
	s_add_u32 s98, s18, 0x80000
	s_addc_u32 s99, s19, 0
	s_nop 0
	global_load_dwordx4 v[220:223], v187, s[98:99]
	global_load_dwordx4 v[224:227], v187, s[98:99] offset:256
	s_add_u32 s98, s18, 0x90000
	s_addc_u32 s99, s19, 0
	s_nop 0
	global_load_dwordx4 v[228:231], v187, s[98:99]
	global_load_dwordx4 v[232:235], v187, s[98:99] offset:256
	s_add_u32 s98, s18, 0xa0000
	s_addc_u32 s99, s19, 0
	s_nop 0
	global_load_dwordx4 v[236:239], v187, s[98:99]
	global_load_dwordx4 v[240:243], v187, s[98:99] offset:256
	s_add_u32 s98, s18, 0xb0000
	s_addc_u32 s99, s19, 0
	s_nop 0
	global_load_dwordx4 v[244:247], v187, s[98:99]
	global_load_dwordx4 v[248:251], v187, s[98:99] offset:256
	s_waitcnt vmcnt(15)
	v_fmamk_f32 v184, v164, 0x3a000000, v177
	v_rcp_f32_e32 v184, v184
	v_and_b32_e32 v129, 0xffff0000, v188
	v_lshlrev_b32_e32 v128, 16, v188
	v_and_b32_e32 v131, 0xffff0000, v189
	v_lshlrev_b32_e32 v130, 16, v189
	v_and_b32_e32 v133, 0xffff0000, v190
	v_lshlrev_b32_e32 v132, 16, v190
	v_and_b32_e32 v135, 0xffff0000, v191
	v_lshlrev_b32_e32 v134, 16, v191
	v_pk_mul_f32 v[128:129], v[148:149], v[128:129]
	v_pk_mul_f32 v[130:131], v[150:151], v[130:131]
	v_pk_mul_f32 v[132:133], v[152:153], v[132:133]
	v_pk_mul_f32 v[134:135], v[154:155], v[134:135]
	v_pk_fma_f32 v[124:125], v[124:125], v[184:185], v[128:129] op_sel_hi:[1,0,1]
	v_pk_fma_f32 v[126:127], v[126:127], v[184:185], v[130:131] op_sel_hi:[1,0,1]
	v_pk_fma_f32 v[120:121], v[120:121], v[184:185], v[132:133] op_sel_hi:[1,0,1]
	v_pk_fma_f32 v[122:123], v[122:123], v[184:185], v[134:135] op_sel_hi:[1,0,1]
	v_pk_mul_f32 v[182:183], v[124:125], v[124:125]
	v_pk_fma_f32 v[182:183], v[126:127], v[126:127], v[182:183]
	v_pk_fma_f32 v[182:183], v[120:121], v[120:121], v[182:183]
	v_pk_fma_f32 v[182:183], v[122:123], v[122:123], v[182:183]
	s_waitcnt vmcnt(14)
	v_and_b32_e32 v129, 0xffff0000, v192
	v_lshlrev_b32_e32 v128, 16, v192
	v_and_b32_e32 v131, 0xffff0000, v193
	v_lshlrev_b32_e32 v130, 16, v193
	v_and_b32_e32 v133, 0xffff0000, v194
	v_lshlrev_b32_e32 v132, 16, v194
	v_and_b32_e32 v135, 0xffff0000, v195
	v_lshlrev_b32_e32 v134, 16, v195
	v_pk_mul_f32 v[128:129], v[156:157], v[128:129]
	v_pk_mul_f32 v[130:131], v[158:159], v[130:131]
	v_pk_mul_f32 v[132:133], v[160:161], v[132:133]
	v_pk_mul_f32 v[134:135], v[162:163], v[134:135]
	v_pk_fma_f32 v[116:117], v[116:117], v[184:185], v[128:129] op_sel_hi:[1,0,1]
	v_pk_fma_f32 v[118:119], v[118:119], v[184:185], v[130:131] op_sel_hi:[1,0,1]
	v_pk_fma_f32 v[112:113], v[112:113], v[184:185], v[132:133] op_sel_hi:[1,0,1]
	v_pk_fma_f32 v[114:115], v[114:115], v[184:185], v[134:135] op_sel_hi:[1,0,1]
	v_pk_fma_f32 v[182:183], v[116:117], v[116:117], v[182:183]
	v_pk_fma_f32 v[182:183], v[118:119], v[118:119], v[182:183]
	v_pk_fma_f32 v[182:183], v[112:113], v[112:113], v[182:183]
	v_pk_fma_f32 v[182:183], v[114:115], v[114:115], v[182:183]
	v_add_f32_e32 v164, v182, v183
	s_waitcnt vmcnt(13)
	v_fmamk_f32 v184, v165, 0x3a000000, v177
	v_rcp_f32_e32 v184, v184
	v_and_b32_e32 v129, 0xffff0000, v196
	v_lshlrev_b32_e32 v128, 16, v196
	v_and_b32_e32 v131, 0xffff0000, v197
	v_lshlrev_b32_e32 v130, 16, v197
	v_and_b32_e32 v133, 0xffff0000, v198
	v_lshlrev_b32_e32 v132, 16, v198
	v_and_b32_e32 v135, 0xffff0000, v199
	v_lshlrev_b32_e32 v134, 16, v199
	v_pk_mul_f32 v[128:129], v[148:149], v[128:129]
	v_pk_mul_f32 v[130:131], v[150:151], v[130:131]
	v_pk_mul_f32 v[132:133], v[152:153], v[132:133]
	v_pk_mul_f32 v[134:135], v[154:155], v[134:135]
	v_pk_fma_f32 v[108:109], v[108:109], v[184:185], v[128:129] op_sel_hi:[1,0,1]
	v_pk_fma_f32 v[110:111], v[110:111], v[184:185], v[130:131] op_sel_hi:[1,0,1]
	v_pk_fma_f32 v[104:105], v[104:105], v[184:185], v[132:133] op_sel_hi:[1,0,1]
	v_pk_fma_f32 v[106:107], v[106:107], v[184:185], v[134:135] op_sel_hi:[1,0,1]
	v_pk_mul_f32 v[182:183], v[108:109], v[108:109]
	v_pk_fma_f32 v[182:183], v[110:111], v[110:111], v[182:183]
	v_pk_fma_f32 v[182:183], v[104:105], v[104:105], v[182:183]
	v_pk_fma_f32 v[182:183], v[106:107], v[106:107], v[182:183]
	s_waitcnt vmcnt(12)
	v_and_b32_e32 v129, 0xffff0000, v200
	v_lshlrev_b32_e32 v128, 16, v200
	v_and_b32_e32 v131, 0xffff0000, v201
	v_lshlrev_b32_e32 v130, 16, v201
	v_and_b32_e32 v133, 0xffff0000, v202
	v_lshlrev_b32_e32 v132, 16, v202
	v_and_b32_e32 v135, 0xffff0000, v203
	v_lshlrev_b32_e32 v134, 16, v203
	v_pk_mul_f32 v[128:129], v[156:157], v[128:129]
	v_pk_mul_f32 v[130:131], v[158:159], v[130:131]
	v_pk_mul_f32 v[132:133], v[160:161], v[132:133]
	v_pk_mul_f32 v[134:135], v[162:163], v[134:135]
	v_pk_fma_f32 v[100:101], v[100:101], v[184:185], v[128:129] op_sel_hi:[1,0,1]
	v_pk_fma_f32 v[102:103], v[102:103], v[184:185], v[130:131] op_sel_hi:[1,0,1]
	v_pk_fma_f32 v[96:97], v[96:97], v[184:185], v[132:133] op_sel_hi:[1,0,1]
	v_pk_fma_f32 v[98:99], v[98:99], v[184:185], v[134:135] op_sel_hi:[1,0,1]
	v_pk_fma_f32 v[182:183], v[100:101], v[100:101], v[182:183]
	v_pk_fma_f32 v[182:183], v[102:103], v[102:103], v[182:183]
	v_pk_fma_f32 v[182:183], v[96:97], v[96:97], v[182:183]
	v_pk_fma_f32 v[182:183], v[98:99], v[98:99], v[182:183]
	v_add_f32_e32 v165, v182, v183
	s_waitcnt vmcnt(11)
	v_fmamk_f32 v184, v166, 0x3a000000, v177
	v_rcp_f32_e32 v184, v184
	v_and_b32_e32 v129, 0xffff0000, v204
	v_lshlrev_b32_e32 v128, 16, v204
	v_and_b32_e32 v131, 0xffff0000, v205
	v_lshlrev_b32_e32 v130, 16, v205
	v_and_b32_e32 v133, 0xffff0000, v206
	v_lshlrev_b32_e32 v132, 16, v206
	v_and_b32_e32 v135, 0xffff0000, v207
	v_lshlrev_b32_e32 v134, 16, v207
	v_pk_mul_f32 v[128:129], v[148:149], v[128:129]
	v_pk_mul_f32 v[130:131], v[150:151], v[130:131]
	v_pk_mul_f32 v[132:133], v[152:153], v[132:133]
	v_pk_mul_f32 v[134:135], v[154:155], v[134:135]
	v_pk_fma_f32 v[92:93], v[92:93], v[184:185], v[128:129] op_sel_hi:[1,0,1]
	v_pk_fma_f32 v[94:95], v[94:95], v[184:185], v[130:131] op_sel_hi:[1,0,1]
	v_pk_fma_f32 v[88:89], v[88:89], v[184:185], v[132:133] op_sel_hi:[1,0,1]
	v_pk_fma_f32 v[90:91], v[90:91], v[184:185], v[134:135] op_sel_hi:[1,0,1]
	v_pk_mul_f32 v[182:183], v[92:93], v[92:93]
	v_pk_fma_f32 v[182:183], v[94:95], v[94:95], v[182:183]
	v_pk_fma_f32 v[182:183], v[88:89], v[88:89], v[182:183]
	v_pk_fma_f32 v[182:183], v[90:91], v[90:91], v[182:183]
	s_waitcnt vmcnt(10)
	v_and_b32_e32 v129, 0xffff0000, v208
	v_lshlrev_b32_e32 v128, 16, v208
	v_and_b32_e32 v131, 0xffff0000, v209
	v_lshlrev_b32_e32 v130, 16, v209
	v_and_b32_e32 v133, 0xffff0000, v210
	v_lshlrev_b32_e32 v132, 16, v210
	v_and_b32_e32 v135, 0xffff0000, v211
	v_lshlrev_b32_e32 v134, 16, v211
	v_pk_mul_f32 v[128:129], v[156:157], v[128:129]
	v_pk_mul_f32 v[130:131], v[158:159], v[130:131]
	v_pk_mul_f32 v[132:133], v[160:161], v[132:133]
	v_pk_mul_f32 v[134:135], v[162:163], v[134:135]
	v_pk_fma_f32 v[84:85], v[84:85], v[184:185], v[128:129] op_sel_hi:[1,0,1]
	v_pk_fma_f32 v[86:87], v[86:87], v[184:185], v[130:131] op_sel_hi:[1,0,1]
	v_pk_fma_f32 v[80:81], v[80:81], v[184:185], v[132:133] op_sel_hi:[1,0,1]
	v_pk_fma_f32 v[82:83], v[82:83], v[184:185], v[134:135] op_sel_hi:[1,0,1]
	v_pk_fma_f32 v[182:183], v[84:85], v[84:85], v[182:183]
	v_pk_fma_f32 v[182:183], v[86:87], v[86:87], v[182:183]
	v_pk_fma_f32 v[182:183], v[80:81], v[80:81], v[182:183]
	v_pk_fma_f32 v[182:183], v[82:83], v[82:83], v[182:183]
	v_add_f32_e32 v166, v182, v183
	s_waitcnt vmcnt(9)
	v_fmamk_f32 v184, v167, 0x3a000000, v177
	v_rcp_f32_e32 v184, v184
	v_and_b32_e32 v129, 0xffff0000, v212
	v_lshlrev_b32_e32 v128, 16, v212
	v_and_b32_e32 v131, 0xffff0000, v213
	v_lshlrev_b32_e32 v130, 16, v213
	v_and_b32_e32 v133, 0xffff0000, v214
	v_lshlrev_b32_e32 v132, 16, v214
	v_and_b32_e32 v135, 0xffff0000, v215
	v_lshlrev_b32_e32 v134, 16, v215
	v_pk_mul_f32 v[128:129], v[148:149], v[128:129]
	v_pk_mul_f32 v[130:131], v[150:151], v[130:131]
	v_pk_mul_f32 v[132:133], v[152:153], v[132:133]
	v_pk_mul_f32 v[134:135], v[154:155], v[134:135]
	v_pk_fma_f32 v[76:77], v[76:77], v[184:185], v[128:129] op_sel_hi:[1,0,1]
	v_pk_fma_f32 v[78:79], v[78:79], v[184:185], v[130:131] op_sel_hi:[1,0,1]
	v_pk_fma_f32 v[72:73], v[72:73], v[184:185], v[132:133] op_sel_hi:[1,0,1]
	v_pk_fma_f32 v[74:75], v[74:75], v[184:185], v[134:135] op_sel_hi:[1,0,1]
	v_pk_mul_f32 v[182:183], v[76:77], v[76:77]
	v_pk_fma_f32 v[182:183], v[78:79], v[78:79], v[182:183]
	v_pk_fma_f32 v[182:183], v[72:73], v[72:73], v[182:183]
	v_pk_fma_f32 v[182:183], v[74:75], v[74:75], v[182:183]
	s_waitcnt vmcnt(8)
	v_and_b32_e32 v129, 0xffff0000, v216
	v_lshlrev_b32_e32 v128, 16, v216
	v_and_b32_e32 v131, 0xffff0000, v217
	v_lshlrev_b32_e32 v130, 16, v217
	v_and_b32_e32 v133, 0xffff0000, v218
	v_lshlrev_b32_e32 v132, 16, v218
	v_and_b32_e32 v135, 0xffff0000, v219
	v_lshlrev_b32_e32 v134, 16, v219
	v_pk_mul_f32 v[128:129], v[156:157], v[128:129]
	v_pk_mul_f32 v[130:131], v[158:159], v[130:131]
	v_pk_mul_f32 v[132:133], v[160:161], v[132:133]
	v_pk_mul_f32 v[134:135], v[162:163], v[134:135]
	v_pk_fma_f32 v[68:69], v[68:69], v[184:185], v[128:129] op_sel_hi:[1,0,1]
	v_pk_fma_f32 v[70:71], v[70:71], v[184:185], v[130:131] op_sel_hi:[1,0,1]
	v_pk_fma_f32 v[64:65], v[64:65], v[184:185], v[132:133] op_sel_hi:[1,0,1]
	v_pk_fma_f32 v[66:67], v[66:67], v[184:185], v[134:135] op_sel_hi:[1,0,1]
	v_pk_fma_f32 v[182:183], v[68:69], v[68:69], v[182:183]
	v_pk_fma_f32 v[182:183], v[70:71], v[70:71], v[182:183]
	v_pk_fma_f32 v[182:183], v[64:65], v[64:65], v[182:183]
	v_pk_fma_f32 v[182:183], v[66:67], v[66:67], v[182:183]
	v_add_f32_e32 v167, v182, v183
	s_waitcnt vmcnt(7)
	v_fmamk_f32 v184, v168, 0x3a000000, v177
	v_rcp_f32_e32 v184, v184
	v_and_b32_e32 v129, 0xffff0000, v220
	v_lshlrev_b32_e32 v128, 16, v220
	v_and_b32_e32 v131, 0xffff0000, v221
	v_lshlrev_b32_e32 v130, 16, v221
	v_and_b32_e32 v133, 0xffff0000, v222
	v_lshlrev_b32_e32 v132, 16, v222
	v_and_b32_e32 v135, 0xffff0000, v223
	v_lshlrev_b32_e32 v134, 16, v223
	v_pk_mul_f32 v[128:129], v[148:149], v[128:129]
	v_pk_mul_f32 v[130:131], v[150:151], v[130:131]
	v_pk_mul_f32 v[132:133], v[152:153], v[132:133]
	v_pk_mul_f32 v[134:135], v[154:155], v[134:135]
	v_pk_fma_f32 v[60:61], v[60:61], v[184:185], v[128:129] op_sel_hi:[1,0,1]
	v_pk_fma_f32 v[62:63], v[62:63], v[184:185], v[130:131] op_sel_hi:[1,0,1]
	v_pk_fma_f32 v[56:57], v[56:57], v[184:185], v[132:133] op_sel_hi:[1,0,1]
	v_pk_fma_f32 v[58:59], v[58:59], v[184:185], v[134:135] op_sel_hi:[1,0,1]
	v_pk_mul_f32 v[182:183], v[60:61], v[60:61]
	v_pk_fma_f32 v[182:183], v[62:63], v[62:63], v[182:183]
	v_pk_fma_f32 v[182:183], v[56:57], v[56:57], v[182:183]
	v_pk_fma_f32 v[182:183], v[58:59], v[58:59], v[182:183]
	s_waitcnt vmcnt(6)
	v_and_b32_e32 v129, 0xffff0000, v224
	v_lshlrev_b32_e32 v128, 16, v224
	v_and_b32_e32 v131, 0xffff0000, v225
	v_lshlrev_b32_e32 v130, 16, v225
	v_and_b32_e32 v133, 0xffff0000, v226
	v_lshlrev_b32_e32 v132, 16, v226
	v_and_b32_e32 v135, 0xffff0000, v227
	v_lshlrev_b32_e32 v134, 16, v227
	v_pk_mul_f32 v[128:129], v[156:157], v[128:129]
	v_pk_mul_f32 v[130:131], v[158:159], v[130:131]
	v_pk_mul_f32 v[132:133], v[160:161], v[132:133]
	v_pk_mul_f32 v[134:135], v[162:163], v[134:135]
	v_pk_fma_f32 v[52:53], v[52:53], v[184:185], v[128:129] op_sel_hi:[1,0,1]
	v_pk_fma_f32 v[54:55], v[54:55], v[184:185], v[130:131] op_sel_hi:[1,0,1]
	v_pk_fma_f32 v[48:49], v[48:49], v[184:185], v[132:133] op_sel_hi:[1,0,1]
	v_pk_fma_f32 v[50:51], v[50:51], v[184:185], v[134:135] op_sel_hi:[1,0,1]
	v_pk_fma_f32 v[182:183], v[52:53], v[52:53], v[182:183]
	v_pk_fma_f32 v[182:183], v[54:55], v[54:55], v[182:183]
	v_pk_fma_f32 v[182:183], v[48:49], v[48:49], v[182:183]
	v_pk_fma_f32 v[182:183], v[50:51], v[50:51], v[182:183]
	v_add_f32_e32 v168, v182, v183
	s_waitcnt vmcnt(5)
	v_fmamk_f32 v184, v169, 0x3a000000, v177
	v_rcp_f32_e32 v184, v184
	v_and_b32_e32 v129, 0xffff0000, v228
	v_lshlrev_b32_e32 v128, 16, v228
	v_and_b32_e32 v131, 0xffff0000, v229
	v_lshlrev_b32_e32 v130, 16, v229
	v_and_b32_e32 v133, 0xffff0000, v230
	v_lshlrev_b32_e32 v132, 16, v230
	v_and_b32_e32 v135, 0xffff0000, v231
	v_lshlrev_b32_e32 v134, 16, v231
	v_pk_mul_f32 v[128:129], v[148:149], v[128:129]
	v_pk_mul_f32 v[130:131], v[150:151], v[130:131]
	v_pk_mul_f32 v[132:133], v[152:153], v[132:133]
	v_pk_mul_f32 v[134:135], v[154:155], v[134:135]
	v_pk_fma_f32 v[44:45], v[44:45], v[184:185], v[128:129] op_sel_hi:[1,0,1]
	v_pk_fma_f32 v[46:47], v[46:47], v[184:185], v[130:131] op_sel_hi:[1,0,1]
	v_pk_fma_f32 v[40:41], v[40:41], v[184:185], v[132:133] op_sel_hi:[1,0,1]
	v_pk_fma_f32 v[42:43], v[42:43], v[184:185], v[134:135] op_sel_hi:[1,0,1]
	v_pk_mul_f32 v[182:183], v[44:45], v[44:45]
	v_pk_fma_f32 v[182:183], v[46:47], v[46:47], v[182:183]
	v_pk_fma_f32 v[182:183], v[40:41], v[40:41], v[182:183]
	v_pk_fma_f32 v[182:183], v[42:43], v[42:43], v[182:183]
	s_waitcnt vmcnt(4)
	v_and_b32_e32 v129, 0xffff0000, v232
	v_lshlrev_b32_e32 v128, 16, v232
	v_and_b32_e32 v131, 0xffff0000, v233
	v_lshlrev_b32_e32 v130, 16, v233
	v_and_b32_e32 v133, 0xffff0000, v234
	v_lshlrev_b32_e32 v132, 16, v234
	v_and_b32_e32 v135, 0xffff0000, v235
	v_lshlrev_b32_e32 v134, 16, v235
	v_pk_mul_f32 v[128:129], v[156:157], v[128:129]
	v_pk_mul_f32 v[130:131], v[158:159], v[130:131]
	v_pk_mul_f32 v[132:133], v[160:161], v[132:133]
	v_pk_mul_f32 v[134:135], v[162:163], v[134:135]
	v_pk_fma_f32 v[36:37], v[36:37], v[184:185], v[128:129] op_sel_hi:[1,0,1]
	v_pk_fma_f32 v[38:39], v[38:39], v[184:185], v[130:131] op_sel_hi:[1,0,1]
	v_pk_fma_f32 v[32:33], v[32:33], v[184:185], v[132:133] op_sel_hi:[1,0,1]
	v_pk_fma_f32 v[34:35], v[34:35], v[184:185], v[134:135] op_sel_hi:[1,0,1]
	v_pk_fma_f32 v[182:183], v[36:37], v[36:37], v[182:183]
	v_pk_fma_f32 v[182:183], v[38:39], v[38:39], v[182:183]
	v_pk_fma_f32 v[182:183], v[32:33], v[32:33], v[182:183]
	v_pk_fma_f32 v[182:183], v[34:35], v[34:35], v[182:183]
	v_add_f32_e32 v169, v182, v183
	s_waitcnt vmcnt(3)
	v_fmamk_f32 v184, v170, 0x3a000000, v177
	v_rcp_f32_e32 v184, v184
	v_and_b32_e32 v129, 0xffff0000, v236
	v_lshlrev_b32_e32 v128, 16, v236
	v_and_b32_e32 v131, 0xffff0000, v237
	v_lshlrev_b32_e32 v130, 16, v237
	v_and_b32_e32 v133, 0xffff0000, v238
	v_lshlrev_b32_e32 v132, 16, v238
	v_and_b32_e32 v135, 0xffff0000, v239
	v_lshlrev_b32_e32 v134, 16, v239
	v_pk_mul_f32 v[128:129], v[148:149], v[128:129]
	v_pk_mul_f32 v[130:131], v[150:151], v[130:131]
	v_pk_mul_f32 v[132:133], v[152:153], v[132:133]
	v_pk_mul_f32 v[134:135], v[154:155], v[134:135]
	v_pk_fma_f32 v[28:29], v[28:29], v[184:185], v[128:129] op_sel_hi:[1,0,1]
	v_pk_fma_f32 v[30:31], v[30:31], v[184:185], v[130:131] op_sel_hi:[1,0,1]
	v_pk_fma_f32 v[24:25], v[24:25], v[184:185], v[132:133] op_sel_hi:[1,0,1]
	v_pk_fma_f32 v[26:27], v[26:27], v[184:185], v[134:135] op_sel_hi:[1,0,1]
	v_pk_mul_f32 v[182:183], v[28:29], v[28:29]
	v_pk_fma_f32 v[182:183], v[30:31], v[30:31], v[182:183]
	v_pk_fma_f32 v[182:183], v[24:25], v[24:25], v[182:183]
	v_pk_fma_f32 v[182:183], v[26:27], v[26:27], v[182:183]
	s_waitcnt vmcnt(2)
	v_and_b32_e32 v129, 0xffff0000, v240
	v_lshlrev_b32_e32 v128, 16, v240
	v_and_b32_e32 v131, 0xffff0000, v241
	v_lshlrev_b32_e32 v130, 16, v241
	v_and_b32_e32 v133, 0xffff0000, v242
	v_lshlrev_b32_e32 v132, 16, v242
	v_and_b32_e32 v135, 0xffff0000, v243
	v_lshlrev_b32_e32 v134, 16, v243
	v_pk_mul_f32 v[128:129], v[156:157], v[128:129]
	v_pk_mul_f32 v[130:131], v[158:159], v[130:131]
	v_pk_mul_f32 v[132:133], v[160:161], v[132:133]
	v_pk_mul_f32 v[134:135], v[162:163], v[134:135]
	v_pk_fma_f32 v[20:21], v[20:21], v[184:185], v[128:129] op_sel_hi:[1,0,1]
	v_pk_fma_f32 v[22:23], v[22:23], v[184:185], v[130:131] op_sel_hi:[1,0,1]
	v_pk_fma_f32 v[16:17], v[16:17], v[184:185], v[132:133] op_sel_hi:[1,0,1]
	v_pk_fma_f32 v[18:19], v[18:19], v[184:185], v[134:135] op_sel_hi:[1,0,1]
	v_pk_fma_f32 v[182:183], v[20:21], v[20:21], v[182:183]
	v_pk_fma_f32 v[182:183], v[22:23], v[22:23], v[182:183]
	v_pk_fma_f32 v[182:183], v[16:17], v[16:17], v[182:183]
	v_pk_fma_f32 v[182:183], v[18:19], v[18:19], v[182:183]
	v_add_f32_e32 v170, v182, v183
	s_waitcnt vmcnt(1)
	v_fmamk_f32 v184, v171, 0x3a000000, v177
	v_rcp_f32_e32 v184, v184
	v_and_b32_e32 v129, 0xffff0000, v244
	v_lshlrev_b32_e32 v128, 16, v244
	v_and_b32_e32 v131, 0xffff0000, v245
	v_lshlrev_b32_e32 v130, 16, v245
	v_and_b32_e32 v133, 0xffff0000, v246
	v_lshlrev_b32_e32 v132, 16, v246
	v_and_b32_e32 v135, 0xffff0000, v247
	v_lshlrev_b32_e32 v134, 16, v247
	v_pk_mul_f32 v[128:129], v[148:149], v[128:129]
	v_pk_mul_f32 v[130:131], v[150:151], v[130:131]
	v_pk_mul_f32 v[132:133], v[152:153], v[132:133]
	v_pk_mul_f32 v[134:135], v[154:155], v[134:135]
	v_pk_fma_f32 v[12:13], v[12:13], v[184:185], v[128:129] op_sel_hi:[1,0,1]
	v_pk_fma_f32 v[14:15], v[14:15], v[184:185], v[130:131] op_sel_hi:[1,0,1]
	v_pk_fma_f32 v[8:9], v[8:9], v[184:185], v[132:133] op_sel_hi:[1,0,1]
	v_pk_fma_f32 v[10:11], v[10:11], v[184:185], v[134:135] op_sel_hi:[1,0,1]
	v_pk_mul_f32 v[182:183], v[12:13], v[12:13]
	v_pk_fma_f32 v[182:183], v[14:15], v[14:15], v[182:183]
	v_pk_fma_f32 v[182:183], v[8:9], v[8:9], v[182:183]
	v_pk_fma_f32 v[182:183], v[10:11], v[10:11], v[182:183]
	s_waitcnt vmcnt(0)
	v_and_b32_e32 v129, 0xffff0000, v248
	v_lshlrev_b32_e32 v128, 16, v248
	v_and_b32_e32 v131, 0xffff0000, v249
	v_lshlrev_b32_e32 v130, 16, v249
	v_and_b32_e32 v133, 0xffff0000, v250
	v_lshlrev_b32_e32 v132, 16, v250
	v_and_b32_e32 v135, 0xffff0000, v251
	v_lshlrev_b32_e32 v134, 16, v251
	v_pk_mul_f32 v[128:129], v[156:157], v[128:129]
	v_pk_mul_f32 v[130:131], v[158:159], v[130:131]
	v_pk_mul_f32 v[132:133], v[160:161], v[132:133]
	v_pk_mul_f32 v[134:135], v[162:163], v[134:135]
	v_pk_fma_f32 v[4:5], v[4:5], v[184:185], v[128:129] op_sel_hi:[1,0,1]
	v_pk_fma_f32 v[6:7], v[6:7], v[184:185], v[130:131] op_sel_hi:[1,0,1]
	v_pk_fma_f32 v[0:1], v[0:1], v[184:185], v[132:133] op_sel_hi:[1,0,1]
	v_pk_fma_f32 v[2:3], v[2:3], v[184:185], v[134:135] op_sel_hi:[1,0,1]
	v_pk_fma_f32 v[182:183], v[4:5], v[4:5], v[182:183]
	v_pk_fma_f32 v[182:183], v[6:7], v[6:7], v[182:183]
	v_pk_fma_f32 v[182:183], v[0:1], v[0:1], v[182:183]
	v_pk_fma_f32 v[182:183], v[2:3], v[2:3], v[182:183]
	v_add_f32_e32 v171, v182, v183
	global_load_dwordx4 v[148:151], v252, s[86:87] offset:0
	global_load_dwordx4 v[152:155], v252, s[86:87] offset:16
	global_load_dwordx4 v[156:159], v252, s[86:87] offset:512
	global_load_dwordx4 v[160:163], v252, s[86:87] offset:528
	v_xor_b32_e32 v128, 16, v186
	v_xor_b32_e32 v129, 32, v186
	v_lshlrev_b32_e32 v128, 2, v128
	v_lshlrev_b32_e32 v129, 2, v129
	ds_bpermute_b32 v188, v128, v164
	ds_bpermute_b32 v189, v128, v165
	ds_bpermute_b32 v190, v128, v166
	ds_bpermute_b32 v191, v128, v167
	ds_bpermute_b32 v192, v128, v168
	ds_bpermute_b32 v193, v128, v169
	ds_bpermute_b32 v194, v128, v170
	ds_bpermute_b32 v195, v128, v171
	s_waitcnt lgkmcnt(7)
	v_add_f32_e32 v164, v164, v188
	s_waitcnt lgkmcnt(6)
	v_add_f32_e32 v165, v165, v189
	s_waitcnt lgkmcnt(5)
	v_add_f32_e32 v166, v166, v190
	s_waitcnt lgkmcnt(4)
	v_add_f32_e32 v167, v167, v191
	s_waitcnt lgkmcnt(3)
	v_add_f32_e32 v168, v168, v192
	s_waitcnt lgkmcnt(2)
	v_add_f32_e32 v169, v169, v193
	s_waitcnt lgkmcnt(1)
	v_add_f32_e32 v170, v170, v194
	s_waitcnt lgkmcnt(0)
	v_add_f32_e32 v171, v171, v195
	ds_bpermute_b32 v188, v129, v164
	ds_bpermute_b32 v189, v129, v165
	ds_bpermute_b32 v190, v129, v166
	ds_bpermute_b32 v191, v129, v167
	ds_bpermute_b32 v192, v129, v168
	ds_bpermute_b32 v193, v129, v169
	ds_bpermute_b32 v194, v129, v170
	ds_bpermute_b32 v195, v129, v171
	v_cmp_eq_u32_e32 vcc, 0, v173
	s_and_saveexec_b64 s[36:37], vcc
	s_waitcnt lgkmcnt(7)
	v_add_f32_e32 v164, v164, v188
	global_atomic_add_f32 v253, v164, s[16:17]
	s_waitcnt lgkmcnt(6)
	v_add_f32_e32 v165, v165, v189
	global_atomic_add_f32 v253, v165, s[16:17] offset:64
	s_waitcnt lgkmcnt(5)
	v_add_f32_e32 v166, v166, v190
	global_atomic_add_f32 v253, v166, s[16:17] offset:128
	s_waitcnt lgkmcnt(4)
	v_add_f32_e32 v167, v167, v191
	global_atomic_add_f32 v253, v167, s[16:17] offset:192
	s_waitcnt lgkmcnt(3)
	v_add_f32_e32 v168, v168, v192
	global_atomic_add_f32 v253, v168, s[16:17] offset:512
	s_waitcnt lgkmcnt(2)
	v_add_f32_e32 v169, v169, v193
	global_atomic_add_f32 v253, v169, s[16:17] offset:576
	s_waitcnt lgkmcnt(1)
	v_add_f32_e32 v170, v170, v194
	global_atomic_add_f32 v253, v170, s[16:17] offset:640
	s_waitcnt lgkmcnt(0)
	v_add_f32_e32 v171, v171, v195
	global_atomic_add_f32 v253, v171, s[16:17] offset:704
	s_or_b64 exec, exec, s[36:37]
	s_lshl_b32 s2, s2, 6
	s_ashr_i32 s3, s2, 31
	s_lshl_b64 s[2:3], s[2:3], 2
	s_waitcnt vmcnt(0)
	s_add_u32 s24, s42, s2
	s_addc_u32 s25, s43, s3
	v_cmp_eq_u32_e32 vcc, 0, v173
	v_cmp_eq_u32_e64 s[2:3], 0, v172
	s_and_b64 s[30:31], s[2:3], vcc
	v_mov_b32_e32 v181, 1
	s_and_saveexec_b64 s[2:3], s[30:31]
	global_atomic_add v139, v181, s[24:25]
	s_or_b64 exec, exec, s[2:3]
	s_waitcnt vmcnt(0)
	s_barrier
	v_readlane_b32 s2, v254, 6
	s_nop 3
	s_cmp_lg_u32 s2, 0
	s_cbranch_scc1 .Lp6_poll_done
	s_mov_b32 s29, 0x100001
.Lp6_spin:
	global_load_dword v181, v139, s[24:25] sc1
	s_waitcnt vmcnt(0)
	v_readfirstlane_b32 s2, v181
	s_cmp_gt_u32 s2, 63
	s_cbranch_scc1 .Lp6_poll_done
	s_add_i32 s29, s29, -1
	s_cmp_eq_u32 s29, 0
	s_cbranch_scc1 .Lp6_poll_done
	s_sleep 1
	s_branch .Lp6_spin
.Lp6_poll_done:
	s_barrier
